# retention core: per-chunk state decay applied with 32 scalar v_mul_f32 from the register constant instead of 16 packed v_pk_mul_f32 right behind the state-update MFMAs (instruction selection beside MF
# speedup vs baseline: 1.0151x; 1.0000x over previous
; #define LAS __attribute__((address_space(3)))
; __device__ __forceinline__ bf16_t f2bf(float x) { return (bf16_t)(cvt_pk_bf16(x, x) & 0xffffu); }
; template <int DK, int DVS, bool RET> ...
;     ...
;         {
;             const int tcs = (wid & 1) * 2;
;             f32x4 a0 = {0.f, 0.f, 0.f, 0.f}, a1 = {0.f, 0.f, 0.f, 0.f};
; #pragma unroll
;             for (int kk = 0; kk < DK / 32; ++kk) {
;                 const bf16x8 af = *(const LAS bf16x8*)(QD + (tr * 16 + l16) * LK + kk * 32 + quad * 8);
;                 const bf16x8 b0 = *(const LAS bf16x8*)(KD + (tcs * 16 + l16) * LK + kk * 32 + quad * 8);
;                 const bf16x8 b1 = *(const LAS bf16x8*)(KD + ((tcs + 1) * 16 + l16) * LK + kk * 32 + quad * 8);
;                 a0 = __builtin_amdgcn_mfma_f32_16x16x32_bf16(af, b0, a0, 0, 0, 0);
;                 a1 = __builtin_amdgcn_mfma_f32_16x16x32_bf16(af, b1, a1, 0, 0, 0);
;                 asm volatile("" ::: "memory");
;             }
; #pragma unroll
;             for (int j = 0; j < 4; ++j) { const int p = tr * 16 + quad * 4 + j, s0 = tcs * 16 + l16, s1 = s0 + 16;
;                 AT[p * LS + s0] = f2bf((s0 <= p) ? a0[j] : 0.f); AT[p * LS + s1] = f2bf((s1 <= p) ? a1[j] : 0.f); }
.LBB0_70:
	s_waitcnt lgkmcnt(0)
	s_barrier
	v_add_u32_e32 v198, v175, v123
	ds_read_b128 v[232:235], v218
	ds_read_b128 v[236:239], v174
	ds_read_b128 v[240:243], v174 offset:8448
	ds_read_b128 v[244:247], v198
	ds_read_b128 v[248:251], v219
	s_waitcnt lgkmcnt(3)
	v_mfma_f32_16x16x32_bf16 v[228:231], v[232:235], v[236:239], 0
	ds_read_b128 v[212:215], v218 offset:64
	ds_read_b128 v[236:239], v174 offset:64
	s_waitcnt lgkmcnt(4)
	v_mfma_f32_16x16x32_bf16 v[64:67], v[232:235], v[240:243], 0
	ds_read_b128 v[240:243], v174 offset:8512
	s_waitcnt lgkmcnt(4)
	v_mfma_f32_16x16x32_bf16 v[220:223], v[232:235], v[244:247], 0
	ds_read_b128 v[244:247], v198 offset:64
	s_waitcnt lgkmcnt(4)
	v_mfma_f32_16x16x32_bf16 v[224:227], v[232:235], v[248:251], 0
	ds_read_b128 v[248:251], v219 offset:64
	s_waitcnt lgkmcnt(3)
	v_mfma_f32_16x16x32_bf16 v[228:231], v[212:215], v[236:239], v[228:231]
	ds_read_b128 v[232:235], v218 offset:128
	ds_read_b128 v[236:239], v174 offset:128
	s_waitcnt lgkmcnt(4)
	v_mfma_f32_16x16x32_bf16 v[64:67], v[212:215], v[240:243], v[64:67]
	ds_read_b128 v[240:243], v174 offset:8576
	s_waitcnt lgkmcnt(4)
	v_mfma_f32_16x16x32_bf16 v[220:223], v[212:215], v[244:247], v[220:223]
	ds_read_b128 v[244:247], v198 offset:128
	s_waitcnt lgkmcnt(4)
	v_mfma_f32_16x16x32_bf16 v[224:227], v[212:215], v[248:251], v[224:227]
	ds_read_b128 v[248:251], v219 offset:128
	s_waitcnt lgkmcnt(3)
	v_mfma_f32_16x16x32_bf16 v[228:231], v[232:235], v[236:239], v[228:231]
	ds_read_b128 v[212:215], v218 offset:192
	ds_read_b128 v[236:239], v174 offset:192
	s_waitcnt lgkmcnt(4)
	v_mfma_f32_16x16x32_bf16 v[64:67], v[232:235], v[240:243], v[64:67]
	ds_read_b128 v[240:243], v174 offset:8640
	s_waitcnt lgkmcnt(4)
	v_mfma_f32_16x16x32_bf16 v[220:223], v[232:235], v[244:247], v[220:223]
	ds_read_b128 v[244:247], v198 offset:192
	s_waitcnt lgkmcnt(4)
	v_mfma_f32_16x16x32_bf16 v[224:227], v[232:235], v[248:251], v[224:227]
	ds_read_b128 v[248:251], v219 offset:192
	s_waitcnt lgkmcnt(3)
	v_mfma_f32_16x16x32_bf16 v[228:231], v[212:215], v[236:239], v[228:231]
	ds_read_b128 v[232:235], v218 offset:256
	ds_read_b128 v[236:239], v174 offset:256
	s_waitcnt lgkmcnt(4)
	v_mfma_f32_16x16x32_bf16 v[64:67], v[212:215], v[240:243], v[64:67]
	ds_read_b128 v[240:243], v174 offset:8704
	s_waitcnt lgkmcnt(4)
	v_mfma_f32_16x16x32_bf16 v[220:223], v[212:215], v[244:247], v[220:223]
	ds_read_b128 v[244:247], v198 offset:256
	s_waitcnt lgkmcnt(4)
	v_mfma_f32_16x16x32_bf16 v[224:227], v[212:215], v[248:251], v[224:227]
	ds_read_b128 v[248:251], v219 offset:256
	s_waitcnt lgkmcnt(3)
	v_mfma_f32_16x16x32_bf16 v[228:231], v[232:235], v[236:239], v[228:231]
	ds_read_b128 v[212:215], v218 offset:320
	ds_read_b128 v[236:239], v174 offset:320
	s_waitcnt lgkmcnt(4)
	v_mfma_f32_16x16x32_bf16 v[64:67], v[232:235], v[240:243], v[64:67]
	ds_read_b128 v[240:243], v174 offset:8768
	s_waitcnt lgkmcnt(4)
	v_mfma_f32_16x16x32_bf16 v[220:223], v[232:235], v[244:247], v[220:223]
	ds_read_b128 v[244:247], v198 offset:320
	s_waitcnt lgkmcnt(4)
	v_mfma_f32_16x16x32_bf16 v[224:227], v[232:235], v[248:251], v[224:227]
	ds_read_b128 v[248:251], v219 offset:320
	s_waitcnt lgkmcnt(3)
	v_mfma_f32_16x16x32_bf16 v[228:231], v[212:215], v[236:239], v[228:231]
	ds_read_b128 v[232:235], v218 offset:384
	ds_read_b128 v[236:239], v174 offset:384
	s_waitcnt lgkmcnt(4)
	v_mfma_f32_16x16x32_bf16 v[64:67], v[212:215], v[240:243], v[64:67]
	ds_read_b128 v[240:243], v174 offset:8832
	s_waitcnt lgkmcnt(4)
	v_mfma_f32_16x16x32_bf16 v[220:223], v[212:215], v[244:247], v[220:223]
	ds_read_b128 v[244:247], v198 offset:384
	s_waitcnt lgkmcnt(4)
	v_mfma_f32_16x16x32_bf16 v[224:227], v[212:215], v[248:251], v[224:227]
	ds_read_b128 v[248:251], v219 offset:384
	s_waitcnt lgkmcnt(3)
	v_mfma_f32_16x16x32_bf16 v[228:231], v[232:235], v[236:239], v[228:231]
	ds_read_b128 v[212:215], v218 offset:448
	ds_read_b128 v[236:239], v174 offset:448
	s_waitcnt lgkmcnt(4)
	v_mfma_f32_16x16x32_bf16 v[64:67], v[232:235], v[240:243], v[64:67]
	ds_read_b128 v[240:243], v174 offset:8896
	s_waitcnt lgkmcnt(4)
	v_mfma_f32_16x16x32_bf16 v[220:223], v[232:235], v[244:247], v[220:223]
	ds_read_b128 v[244:247], v198 offset:448
	s_waitcnt lgkmcnt(4)
	v_mfma_f32_16x16x32_bf16 v[224:227], v[232:235], v[248:251], v[224:227]
	ds_read_b128 v[248:251], v219 offset:448
	s_waitcnt lgkmcnt(3)
	v_mfma_f32_16x16x32_bf16 v[228:231], v[212:215], v[236:239], v[228:231]
	s_waitcnt lgkmcnt(2)
	v_mfma_f32_16x16x32_bf16 v[64:67], v[212:215], v[240:243], v[64:67]
	s_waitcnt lgkmcnt(1)
	v_mfma_f32_16x16x32_bf16 v[220:223], v[212:215], v[244:247], v[220:223]
	s_waitcnt lgkmcnt(0)
	v_mfma_f32_16x16x32_bf16 v[224:227], v[212:215], v[248:251], v[224:227]
	s_nop 6
	v_cvt_pk_bf16_f32 v64, v64, s0
	v_cndmask_b32_e64 v64, v64, 0, s[8:9]
	ds_write_b16 v199, v64 offset:32
	v_cvt_pk_bf16_f32 v64, v229, s0
	v_cndmask_b32_e64 v64, v64, 0, s[10:11]
	ds_write_b16 v200, v64
	v_cvt_pk_bf16_f32 v64, v65, s0
	v_cndmask_b32_e64 v64, v64, 0, s[12:13]
	ds_write_b16 v200, v64 offset:32
	v_cvt_pk_bf16_f32 v64, v230, s0
	v_cndmask_b32_e64 v64, v64, 0, s[14:15]
	ds_write_b16 v201, v64
	v_cvt_pk_bf16_f32 v64, v66, s0
	v_cndmask_b32_e64 v64, v64, 0, s[16:17]
	ds_write_b16 v201, v64 offset:32
	v_cvt_pk_bf16_f32 v64, v231, s0
	v_cndmask_b32_e64 v64, v64, 0, s[18:19]
	v_cvt_pk_bf16_f32 v198, v228, s0
	ds_write_b16 v202, v64
	v_cvt_pk_bf16_f32 v64, v67, s0
	v_cndmask_b32_e64 v198, v198, 0, s[6:7]
	v_cndmask_b32_e64 v64, v64, 0, s[20:21]
	ds_write_b16 v199, v198
	ds_write_b16 v202, v64 offset:32
	s_waitcnt lgkmcnt(0)
	s_barrier
; #define LAS __attribute__((address_space(3)))
; template <int DK, int DVS, bool RET> ...
;     ...
;             for (int j = 0; j < 4; ++j) { const int p = tr * 16 + quad * 4 + j, s0 = tcs * 16 + l16, s1 = s0 + 16;
;                 AT[p * LS + s0] = f2bf((s0 <= p) ? a0[j] : 0.f); AT[p * LS + s1] = f2bf((s1 <= p) ? a1[j] : 0.f); }
;         }
;         GLA_BAR();
; #pragma unroll
;         for (int t = 0; t < NOT; ++t) { const int tc = (wid & 1) * NOT + t; f32x4 acc = {0.f, 0.f, 0.f, 0.f};
; #pragma unroll
;             for (int kk = 0; kk < DK / 32; ++kk) {
;                 const bf16x8 af = *(const LAS bf16x8*)(QD + (tr * 16 + l16) * LK + kk * 32 + quad * 8);
;                 const bf16x8 bf = *(const LAS bf16x8*)(STB + (tc * 16 + l16) * LK + kk * 32 + quad * 8);
;                 acc = __builtin_amdgcn_mfma_f32_16x16x32_bf16(af, bf, acc, 0, 0, 0);
;                 if ((kk & 3) == 3) asm volatile("" ::: "memory"); }
;             { s16x4 v00, v01, v10, v11; const int vb = vtr + tc * 32;
;                 TRR(v00, vb, 0); TRR(v01, vb, 4 * LV * 2); TRR(v10, vb, 32 * LV * 2); TRR(v11, vb, 36 * LV * 2);
;                 const bf16x8 a0 = *(const LAS bf16x8*)(AT + (tr * 16 + l16) * LS + quad * 8), a1 = *(const LAS bf16x8*)(AT + (tr * 16 + l16) * LS + 32 + quad * 8);
;                 asm volatile("s_waitcnt lgkmcnt(0)" ::: "memory"); __builtin_amdgcn_sched_barrier(0);
;                 acc = __builtin_amdgcn_mfma_f32_16x16x32_bf16(a0, TRFRAG(v00, v01), acc, 0, 0, 0);
;                 acc = __builtin_amdgcn_mfma_f32_16x16x32_bf16(a1, TRFRAG(v10, v11), acc, 0, 0, 0); }
; #pragma unroll
;             for (int j = 0; j < 4; ++j) { const int p = tr * 16 + quad * 4 + j; const long row = R0 + (dir ? 63 - p : p);
;                 ((GAS bf16_t*)Od)[row * ldv + vcol0 + tc * 16 + l16] = f2bf(acc[j]); }
;         }
;         { s16x4 a00, a01, a10, a11; const int vb = vtr + tv * 32;
;             TRR(a00, vb, 0); TRR(a01, vb, 4 * LV * 2); TRR(a10, vb, 32 * LV * 2); TRR(a11, vb, 36 * LV * 2);
; #pragma unroll
;             for (int t0 = 0; t0 < TPW; t0 += 2) {
;                 s16x4 b[2][4];
; #pragma unroll
;                 for (int u = 0; u < 2; ++u) { const int kb = ktr + (kt0 + t0 + u) * 32;
;                     TRR(b[u][0], kb, 0); TRR(b[u][1], kb, 4 * LK * 2); TRR(b[u][2], kb, 32 * LK * 2); TRR(b[u][3], kb, 36 * LK * 2); }
	ds_read_b128 v[248:251], v176
	ds_read_b128 v[212:215], v176 offset:64
	ds_read_b64_tr_b16 v[232:233], v203 offset:0
	ds_read_b64_tr_b16 v[234:235], v203 offset:0x240
	ds_read_b64_tr_b16 v[236:237], v203 offset:0x1200
	ds_read_b64_tr_b16 v[238:239], v203 offset:0x1440
	ds_read_b64_tr_b16 v[240:241], v177 offset:0
	ds_read_b64_tr_b16 v[242:243], v177 offset:0x240
	ds_read_b64_tr_b16 v[244:245], v177 offset:0x1200
	ds_read_b64_tr_b16 v[246:247], v177 offset:0x1440
	s_waitcnt lgkmcnt(6)
	v_mfma_f32_16x16x32_bf16 v[220:223], v[248:251], v[232:235], v[220:223]
	s_waitcnt lgkmcnt(4)
	v_mfma_f32_16x16x32_bf16 v[220:223], v[212:215], v[236:239], v[220:223]
	s_waitcnt lgkmcnt(2)
	v_mfma_f32_16x16x32_bf16 v[224:227], v[248:251], v[240:243], v[224:227]
	s_waitcnt lgkmcnt(0)
	v_mfma_f32_16x16x32_bf16 v[224:227], v[212:215], v[244:247], v[224:227]
	v_lshl_add_u64 v[232:233], s[30:31], 0, v[104:105]
	v_lshlrev_b64 v[232:233], 12, v[232:233]
	v_lshl_add_u64 v[234:235], s[30:31], 0, v[108:109]
	v_lshlrev_b64 v[234:235], 12, v[234:235]
	v_lshl_add_u64 v[236:237], s[30:31], 0, v[110:111]
	v_lshlrev_b64 v[236:237], 12, v[236:237]
	v_lshl_add_u64 v[238:239], s[30:31], 0, v[112:113]
	v_lshlrev_b64 v[238:239], 12, v[238:239]
	s_nop 1
	v_cvt_pk_bf16_f32 v198, v220, s0
	v_lshl_add_u64 v[240:241], v[106:107], 0, v[232:233]
	global_store_short v[240:241], v198, off
	v_cvt_pk_bf16_f32 v242, v221, s0
	v_lshl_add_u64 v[244:245], v[106:107], 0, v[234:235]
	global_store_short v[244:245], v242, off
	v_cvt_pk_bf16_f32 v198, v222, s0
	v_lshl_add_u64 v[240:241], v[106:107], 0, v[236:237]
	global_store_short v[240:241], v198, off
	v_cvt_pk_bf16_f32 v242, v223, s0
	v_lshl_add_u64 v[244:245], v[106:107], 0, v[238:239]
	global_store_short v[244:245], v242, off
	s_nop 3
	v_cvt_pk_bf16_f32 v198, v224, s0
	v_lshl_add_u64 v[240:241], v[114:115], 0, v[232:233]
	global_store_short v[240:241], v198, off
	v_cvt_pk_bf16_f32 v242, v225, s0
	v_lshl_add_u64 v[244:245], v[114:115], 0, v[234:235]
	global_store_short v[244:245], v242, off
	v_cvt_pk_bf16_f32 v198, v226, s0
	v_lshl_add_u64 v[240:241], v[114:115], 0, v[236:237]
	global_store_short v[240:241], v198, off
	v_cvt_pk_bf16_f32 v242, v227, s0
	v_lshl_add_u64 v[244:245], v[114:115], 0, v[238:239]
	global_store_short v[244:245], v242, off
	ds_read_b64_tr_b16 v[64:65], v144 offset:0
	ds_read_b64_tr_b16 v[66:67], v144 offset:0x240
	ds_read_b64_tr_b16 v[228:229], v144 offset:0x1200
	ds_read_b64_tr_b16 v[230:231], v144 offset:0x1440
	ds_read_b64_tr_b16 v[232:233], v83 offset:0
	ds_read_b64_tr_b16 v[234:235], v83 offset:0x840
	ds_read_b64_tr_b16 v[236:237], v83 offset:0x4200
	ds_read_b64_tr_b16 v[238:239], v83 offset:0x4a40
	ds_read_b64_tr_b16 v[240:241], v85 offset:0
	ds_read_b64_tr_b16 v[242:243], v85 offset:0x840
	ds_read_b64_tr_b16 v[244:245], v85 offset:0x4200
	ds_read_b64_tr_b16 v[246:247], v85 offset:0x4a40
	s_waitcnt lgkmcnt(0)
	s_nop 0
	v_mfma_f32_16x16x32_bf16 v[56:59], v[232:235], v[64:67], v[56:59]
	ds_read_b64_tr_b16 v[232:233], v204 offset:0
	ds_read_b64_tr_b16 v[234:235], v204 offset:0x840
	v_mfma_f32_16x16x32_bf16 v[56:59], v[236:239], v[228:231], v[56:59]
	ds_read_b64_tr_b16 v[236:237], v204 offset:0x4200
	ds_read_b64_tr_b16 v[238:239], v204 offset:0x4a40
	v_mfma_f32_16x16x32_bf16 v[60:63], v[240:243], v[64:67], v[60:63]
	ds_read_b64_tr_b16 v[240:241], v205 offset:0
	ds_read_b64_tr_b16 v[242:243], v205 offset:0x840
	v_mfma_f32_16x16x32_bf16 v[60:63], v[244:247], v[228:231], v[60:63]
	ds_read_b64_tr_b16 v[244:245], v205 offset:0x4200
	ds_read_b64_tr_b16 v[246:247], v205 offset:0x4a40
	s_waitcnt lgkmcnt(0)
	v_mfma_f32_16x16x32_bf16 v[48:51], v[232:235], v[64:67], v[48:51]
	ds_read_b64_tr_b16 v[232:233], v206 offset:0
	ds_read_b64_tr_b16 v[234:235], v206 offset:0x840
	v_mfma_f32_16x16x32_bf16 v[48:51], v[236:239], v[228:231], v[48:51]
	ds_read_b64_tr_b16 v[236:237], v206 offset:0x4200
	ds_read_b64_tr_b16 v[238:239], v206 offset:0x4a40
	v_mfma_f32_16x16x32_bf16 v[52:55], v[240:243], v[64:67], v[52:55]
	ds_read_b64_tr_b16 v[240:241], v207 offset:0
	ds_read_b64_tr_b16 v[242:243], v207 offset:0x840
	v_mfma_f32_16x16x32_bf16 v[52:55], v[244:247], v[228:231], v[52:55]
	ds_read_b64_tr_b16 v[244:245], v207 offset:0x4200
	ds_read_b64_tr_b16 v[246:247], v207 offset:0x4a40
	s_waitcnt lgkmcnt(0)
	v_mfma_f32_16x16x32_bf16 v[40:43], v[232:235], v[64:67], v[40:43]
	ds_read_b64_tr_b16 v[232:233], v208 offset:0
	ds_read_b64_tr_b16 v[234:235], v208 offset:0x840
	v_mfma_f32_16x16x32_bf16 v[40:43], v[236:239], v[228:231], v[40:43]
	ds_read_b64_tr_b16 v[236:237], v208 offset:0x4200
	ds_read_b64_tr_b16 v[238:239], v208 offset:0x4a40
	v_mfma_f32_16x16x32_bf16 v[44:47], v[240:243], v[64:67], v[44:47]
	ds_read_b64_tr_b16 v[240:241], v209 offset:0
	ds_read_b64_tr_b16 v[242:243], v209 offset:0x840
	v_mfma_f32_16x16x32_bf16 v[44:47], v[244:247], v[228:231], v[44:47]
	ds_read_b64_tr_b16 v[244:245], v209 offset:0x4200
	ds_read_b64_tr_b16 v[246:247], v209 offset:0x4a40
	s_waitcnt lgkmcnt(0)
	v_mfma_f32_16x16x32_bf16 v[36:39], v[232:235], v[64:67], v[36:39]
	s_add_i32 s42, s42, -1
	s_cmpk_lg_i32 s42, 0xffbc
	s_mov_b32 s45, s36
	v_mfma_f32_16x16x32_bf16 v[0:3], v[240:243], v[64:67], v[0:3]
	v_mfma_f32_16x16x32_bf16 v[36:39], v[236:239], v[228:231], v[36:39]
	v_mfma_f32_16x16x32_bf16 v[0:3], v[244:247], v[228:231], v[0:3]
	v_mul_f32_e32 v58, v173, v58
	v_mul_f32_e32 v59, v173, v59
	v_mul_f32_e32 v56, v173, v56
	v_mul_f32_e32 v57, v173, v57
	v_mul_f32_e32 v62, v173, v62
	v_mul_f32_e32 v63, v173, v63
	v_mul_f32_e32 v60, v173, v60
	v_mul_f32_e32 v61, v173, v61
	v_mul_f32_e32 v50, v173, v50
	v_mul_f32_e32 v51, v173, v51
	v_mul_f32_e32 v48, v173, v48
	v_mul_f32_e32 v49, v173, v49
	v_mul_f32_e32 v54, v173, v54
	v_mul_f32_e32 v55, v173, v55
	v_mul_f32_e32 v52, v173, v52
	v_mul_f32_e32 v53, v173, v53
	v_mul_f32_e32 v42, v173, v42
	v_mul_f32_e32 v43, v173, v43
	v_mul_f32_e32 v40, v173, v40
	v_mul_f32_e32 v41, v173, v41
	v_mul_f32_e32 v46, v173, v46
	v_mul_f32_e32 v47, v173, v47
	v_mul_f32_e32 v44, v173, v44
	v_mul_f32_e32 v45, v173, v45
	v_mul_f32_e32 v38, v173, v38
	v_mul_f32_e32 v39, v173, v39
	v_mul_f32_e32 v36, v173, v36
	v_mul_f32_e32 v37, v173, v37
	v_mul_f32_e32 v2, v173, v2
	v_mul_f32_e32 v3, v173, v3
	v_mul_f32_e32 v0, v173, v0
	v_mul_f32_e32 v1, v173, v1
	s_cbranch_scc0 .LBB0_68
